# MIX-2 queue reordered (lru_prompt scan right after its producers), long items steered to one block per CU by delaying blocks >= 256 at phase start
# speedup vs baseline: 1.1901x; 1.0443x over previous
.LBB0_524:
	s_or_b64 exec, exec, s[2:3]
	s_barrier
	v_readlane_b32 s4, v255, 14
	s_nop 1
	s_cmp_lt_u32 s4, 256
	s_cbranch_scc1 .LBB0_529
	s_sleep 127
	s_sleep 127
	s_sleep 127
	s_branch .LBB0_529

.Lmx_a:
	s_cmp_lt_u32 s21, 808
	s_cbranch_scc0 .Lmx_b
	s_add_u32 s31, s21, 1536
	s_mov_b32 s101, 2
	s_branch .Lmx_disp1
.Lmx_b:
	s_cmp_lt_u32 s21, 840
	s_cbranch_scc0 .Lmx_c
	s_sub_u32 s21, s21, 776
	s_branch .Lmx_waitC2
.Lmx_c:
	s_cmp_lt_u32 s21, 1352
	s_cbranch_scc0 .Lmx_d
	s_add_u32 s31, s21, 1504
	s_mov_b32 s101, 1
	s_branch .Lmx_disp1
.Lmx_d:
	s_cmp_lt_u32 s21, 2000
	s_cbranch_scc0 .Lmx_e
	s_sub_u32 s21, s21, 100
	s_branch .Lmx_go2
.Lmx_e:
	s_cmp_lt_u32 s21, 2512
	s_cbranch_scc0 .Lmx_f
	s_sub_u32 s21, s21, 1388
	s_branch .Lmx_go2
